# W_out and W_q transposes both on the idle blocks at the end of P4 (P5's tail left empty)
# baseline (speedup 1.0000x reference)
.LBB0_658:
	s_cmp_lt_u32 s2, 0x80
	s_cbranch_scc1 .Ltb_done
	s_load_dwordx2 s[30:31], s[0:1], 0x40
	s_load_dwordx2 s[32:33], s[0:1], 0xb0
	s_load_dwordx2 s[34:35], s[0:1], 0xc8
	s_load_dwordx2 s[36:37], s[0:1], 0xd0
	s_load_dwordx2 s[38:39], s[0:1], 0xe0
	s_movk_i32 s3, 384
	v_lshrrev_b32_e32 v0, 4, v204
	v_and_b32_e32 v1, 15, v204
	v_lshlrev_b32_e32 v1, 4, v1
	v_lshrrev_b32_e32 v2, 3, v204
	v_and_b32_e32 v3, 7, v204
	v_add_u32_e32 v8, 0, v0
	v_mul_u32_u24_e32 v8, 0x104, v8
	v_add3_u32 v8, v8, v1, 32
	v_add_u32_e32 v72, 0x4100, v8
	v_add_u32_e32 v9, 16, v0
	v_mul_u32_u24_e32 v9, 0x104, v9
	v_add3_u32 v9, v9, v1, 32
	v_add_u32_e32 v73, 0x4100, v9
	v_add_u32_e32 v10, 32, v0
	v_mul_u32_u24_e32 v10, 0x104, v10
	v_add3_u32 v10, v10, v1, 32
	v_add_u32_e32 v74, 0x4100, v10
	v_add_u32_e32 v11, 48, v0
	v_mul_u32_u24_e32 v11, 0x104, v11
	v_add3_u32 v11, v11, v1, 32
	v_add_u32_e32 v75, 0x4100, v11
	v_mul_u32_u24_e32 v12, 0x820, v3
	v_lshl_add_u32 v12, v2, 2, v12
	v_add_u32_e32 v12, 32, v12
	v_add_u32_e32 v13, 0x410, v12
	v_add_u32_e32 v76, 0x4100, v12
	v_add_u32_e32 v77, 0x4100, v13
	v_lshlrev_b32_e32 v14, 12, v2
	v_lshl_add_u32 v14, v3, 4, v14
	v_add_u32_e32 v78, 0, v0
	v_add_u32_e32 v79, 16, v0
	v_add_u32_e32 v80, 32, v0
	v_add_u32_e32 v81, 48, v0
	s_waitcnt lgkmcnt(0)
	s_sub_u32 s4, s2, 0x80
	s_add_u32 s4, s4, 0x1b00
	s_cmpk_ge_u32 s4, 0x2300
	s_cbranch_scc1 .Ltb_done
	s_mov_b32 s5, s4
